# P8 epilogue: 120 redundant canonicalising v_max before the relu max replaced by equivalent s_nop wait states
# speedup vs baseline: 1.0053x; 1.0003x over previous
.LBB0_898:
	v_max_f32_e32 v125, v125, v125
	v_max_f32_e32 v124, v124, v124
	v_max_f32_e32 v127, v127, v127
	v_max_f32_e32 v126, v126, v126
	v_max_f32_e32 v121, v121, v121
	v_max_f32_e32 v120, v120, v120
	v_max_f32_e32 v123, v123, v123
	v_max_f32_e32 v122, v122, v122
	v_max_f32_e32 v125, 0, v125
	v_max_f32_e32 v124, 0, v124
	v_max_f32_e32 v127, 0, v127
	v_max_f32_e32 v126, 0, v126
	v_max_f32_e32 v121, 0, v121
	v_max_f32_e32 v120, 0, v120
	v_max_f32_e32 v123, 0, v123
	v_max_f32_e32 v122, 0, v122
	v_pk_mul_f32 v[126:127], v[126:127], v[126:127]
	v_pk_mul_f32 v[124:125], v[124:125], v[124:125]
	v_pk_mul_f32 v[152:153], v[122:123], v[122:123]
	v_pk_mul_f32 v[122:123], v[120:121], v[120:121]
	s_nop 7
	v_cvt_pk_bf16_f32 v120, v124, v125
	v_cvt_pk_bf16_f32 v121, v126, v127
	v_cvt_pk_bf16_f32 v122, v122, v123
	v_cvt_pk_bf16_f32 v123, v152, v153
	v_max_f32_e32 v117, 0, v117
	v_max_f32_e32 v116, 0, v116
	v_max_f32_e32 v119, 0, v119
	v_max_f32_e32 v118, 0, v118
	v_max_f32_e32 v113, 0, v113
	v_max_f32_e32 v112, 0, v112
	v_max_f32_e32 v115, 0, v115
	v_max_f32_e32 v114, 0, v114
	ds_write_b128 v147, v[120:123]
	v_pk_mul_f32 v[118:119], v[118:119], v[118:119]
	v_pk_mul_f32 v[116:117], v[116:117], v[116:117]
	v_pk_mul_f32 v[120:121], v[114:115], v[114:115]
	v_pk_mul_f32 v[114:115], v[112:113], v[112:113]
	v_lshl_add_u32 v150, s26, 8, v143
	v_cvt_pk_bf16_f32 v112, v116, v117
	v_cvt_pk_bf16_f32 v113, v118, v119
	v_cvt_pk_bf16_f32 v114, v114, v115
	v_cvt_pk_bf16_f32 v115, v120, v121
	v_ashrrev_i32_e32 v151, 31, v150
	ds_write_b128 v147, v[112:115] offset:64
	v_lshlrev_b64 v[150:151], 13, v[150:151]
	s_lshl_b32 s28, s61, 8
	ds_read_b128 v[114:117], v148
	ds_read_b128 v[118:121], v148 offset:1152
	v_lshl_add_u64 v[150:151], s[4:5], 0, v[150:151]
	s_ashr_i32 s29, s28, 31
	v_lshl_add_u64 v[112:113], s[28:29], 1, v[150:151]
	v_lshl_add_u64 v[112:113], v[112:113], 0, s[8:9]
	v_lshl_add_u64 v[112:113], v[112:113], 0, v[132:133]
	s_waitcnt lgkmcnt(0)
	global_store_dwordx4 v[112:113], v[114:117], off
	s_nop 1
	v_add_co_u32_e32 v114, vcc, s42, v112
	s_nop 5
	v_addc_co_u32_e32 v115, vcc, 0, v113, vcc
	v_max_f32_e32 v109, 0, v109
	v_max_f32_e32 v108, 0, v108
	v_max_f32_e32 v111, 0, v111
	v_max_f32_e32 v110, 0, v110
	v_max_f32_e32 v105, 0, v105
	v_max_f32_e32 v104, 0, v104
	v_max_f32_e32 v107, 0, v107
	v_max_f32_e32 v106, 0, v106
	global_store_dwordx4 v[114:115], v[118:121], off
	v_pk_mul_f32 v[110:111], v[110:111], v[110:111]
	v_pk_mul_f32 v[108:109], v[108:109], v[108:109]
	v_pk_mul_f32 v[114:115], v[106:107], v[106:107]
	v_pk_mul_f32 v[106:107], v[104:105], v[104:105]
	s_nop 7
	v_cvt_pk_bf16_f32 v104, v108, v109
	v_cvt_pk_bf16_f32 v105, v110, v111
	v_cvt_pk_bf16_f32 v106, v106, v107
	v_cvt_pk_bf16_f32 v107, v114, v115
	v_max_f32_e32 v101, 0, v101
	v_max_f32_e32 v100, 0, v100
	v_max_f32_e32 v103, 0, v103
	v_max_f32_e32 v102, 0, v102
	v_max_f32_e32 v97, 0, v97
	v_max_f32_e32 v96, 0, v96
	v_max_f32_e32 v99, 0, v99
	v_max_f32_e32 v98, 0, v98
	ds_write_b128 v147, v[104:107]
	v_pk_mul_f32 v[102:103], v[102:103], v[102:103]
	v_pk_mul_f32 v[100:101], v[100:101], v[100:101]
	v_pk_mul_f32 v[104:105], v[98:99], v[98:99]
	v_pk_mul_f32 v[98:99], v[96:97], v[96:97]
	v_cvt_pk_bf16_f32 v96, v100, v101
	v_cvt_pk_bf16_f32 v97, v102, v103
	v_cvt_pk_bf16_f32 v98, v98, v99
	v_cvt_pk_bf16_f32 v99, v104, v105
	ds_write_b128 v147, v[96:99] offset:64
	ds_read_b128 v[96:99], v148
	ds_read_b128 v[100:103], v148 offset:1152
	v_add_co_u32_e32 v104, vcc, s48, v112
	s_nop 0
	s_nop 0
	v_addc_co_u32_e32 v105, vcc, 0, v113, vcc
	s_waitcnt lgkmcnt(0)
	global_store_dwordx4 v[104:105], v[96:99], off
	s_nop 1
	v_add_co_u32_e32 v96, vcc, s49, v112
	s_nop 4
	v_addc_co_u32_e32 v97, vcc, 0, v113, vcc
	v_max_f32_e32 v93, 0, v93
	v_max_f32_e32 v92, 0, v92
	v_max_f32_e32 v95, 0, v95
	v_max_f32_e32 v94, 0, v94
	v_max_f32_e32 v89, 0, v89
	v_max_f32_e32 v88, 0, v88
	v_max_f32_e32 v91, 0, v91
	v_max_f32_e32 v90, 0, v90
	global_store_dwordx4 v[96:97], v[100:103], off
	v_pk_mul_f32 v[94:95], v[94:95], v[94:95]
	v_pk_mul_f32 v[92:93], v[92:93], v[92:93]
	v_pk_mul_f32 v[96:97], v[90:91], v[90:91]
	v_pk_mul_f32 v[90:91], v[88:89], v[88:89]
	s_nop 7
	v_cvt_pk_bf16_f32 v88, v92, v93
	v_cvt_pk_bf16_f32 v89, v94, v95
	v_cvt_pk_bf16_f32 v90, v90, v91
	v_cvt_pk_bf16_f32 v91, v96, v97
	v_max_f32_e32 v85, 0, v85
	v_max_f32_e32 v84, 0, v84
	v_max_f32_e32 v87, 0, v87
	v_max_f32_e32 v86, 0, v86
	v_max_f32_e32 v81, 0, v81
	v_max_f32_e32 v80, 0, v80
	v_max_f32_e32 v83, 0, v83
	v_max_f32_e32 v82, 0, v82
	ds_write_b128 v147, v[88:91]
	v_pk_mul_f32 v[86:87], v[86:87], v[86:87]
	v_pk_mul_f32 v[84:85], v[84:85], v[84:85]
	v_pk_mul_f32 v[88:89], v[82:83], v[82:83]
	v_pk_mul_f32 v[82:83], v[80:81], v[80:81]
	v_cvt_pk_bf16_f32 v80, v84, v85
	v_cvt_pk_bf16_f32 v81, v86, v87
	v_cvt_pk_bf16_f32 v82, v82, v83
	v_cvt_pk_bf16_f32 v83, v88, v89
	ds_write_b128 v147, v[80:83] offset:64
	ds_read_b128 v[80:83], v148
	ds_read_b128 v[84:87], v148 offset:1152
	v_add_co_u32_e32 v88, vcc, s50, v112
	s_nop 0
	s_nop 0
	v_addc_co_u32_e32 v89, vcc, 0, v113, vcc
	s_waitcnt lgkmcnt(0)
	global_store_dwordx4 v[88:89], v[80:83], off
	s_nop 1
	v_add_co_u32_e32 v80, vcc, s51, v112
	s_nop 4
	v_addc_co_u32_e32 v81, vcc, 0, v113, vcc
	v_max_f32_e32 v77, 0, v77
	v_max_f32_e32 v76, 0, v76
	v_max_f32_e32 v79, 0, v79
	v_max_f32_e32 v78, 0, v78
	v_max_f32_e32 v73, 0, v73
	v_max_f32_e32 v72, 0, v72
	v_max_f32_e32 v75, 0, v75
	v_max_f32_e32 v74, 0, v74
	global_store_dwordx4 v[80:81], v[84:87], off
	v_pk_mul_f32 v[78:79], v[78:79], v[78:79]
	v_pk_mul_f32 v[76:77], v[76:77], v[76:77]
	v_pk_mul_f32 v[80:81], v[74:75], v[74:75]
	v_pk_mul_f32 v[74:75], v[72:73], v[72:73]
	s_nop 7
	v_cvt_pk_bf16_f32 v72, v76, v77
	v_cvt_pk_bf16_f32 v73, v78, v79
	v_cvt_pk_bf16_f32 v74, v74, v75
	v_cvt_pk_bf16_f32 v75, v80, v81
	v_max_f32_e32 v69, 0, v69
	v_max_f32_e32 v68, 0, v68
	v_max_f32_e32 v71, 0, v71
	v_max_f32_e32 v70, 0, v70
	v_max_f32_e32 v65, 0, v65
	v_max_f32_e32 v64, 0, v64
	v_max_f32_e32 v67, 0, v67
	v_max_f32_e32 v66, 0, v66
	ds_write_b128 v147, v[72:75]
	v_pk_mul_f32 v[70:71], v[70:71], v[70:71]
	v_pk_mul_f32 v[68:69], v[68:69], v[68:69]
	v_pk_mul_f32 v[72:73], v[66:67], v[66:67]
	v_pk_mul_f32 v[66:67], v[64:65], v[64:65]
	v_cvt_pk_bf16_f32 v64, v68, v69
	v_cvt_pk_bf16_f32 v65, v70, v71
	v_cvt_pk_bf16_f32 v66, v66, v67
	v_cvt_pk_bf16_f32 v67, v72, v73
	ds_write_b128 v147, v[64:67] offset:64
	ds_read_b128 v[64:67], v148
	ds_read_b128 v[68:71], v148 offset:1152
	v_add_co_u32_e32 v72, vcc, s52, v112
	s_nop 0
	s_nop 0
	v_addc_co_u32_e32 v73, vcc, 0, v113, vcc
	s_waitcnt lgkmcnt(0)
	global_store_dwordx4 v[72:73], v[64:67], off
	s_nop 1
	v_add_co_u32_e32 v64, vcc, s53, v112
	s_nop 4
	v_addc_co_u32_e32 v65, vcc, 0, v113, vcc
	v_max_f32_e32 v61, 0, v61
	v_max_f32_e32 v60, 0, v60
	v_max_f32_e32 v63, 0, v63
	v_max_f32_e32 v62, 0, v62
	v_max_f32_e32 v57, 0, v57
	v_max_f32_e32 v56, 0, v56
	v_max_f32_e32 v59, 0, v59
	v_max_f32_e32 v58, 0, v58
	global_store_dwordx4 v[64:65], v[68:71], off
	v_pk_mul_f32 v[62:63], v[62:63], v[62:63]
	v_pk_mul_f32 v[60:61], v[60:61], v[60:61]
	v_pk_mul_f32 v[64:65], v[58:59], v[58:59]
	v_pk_mul_f32 v[58:59], v[56:57], v[56:57]
	s_nop 7
	v_cvt_pk_bf16_f32 v56, v60, v61
	v_cvt_pk_bf16_f32 v57, v62, v63
	v_cvt_pk_bf16_f32 v58, v58, v59
	v_cvt_pk_bf16_f32 v59, v64, v65
	v_max_f32_e32 v53, 0, v53
	v_max_f32_e32 v52, 0, v52
	v_max_f32_e32 v55, 0, v55
	v_max_f32_e32 v54, 0, v54
	v_max_f32_e32 v49, 0, v49
	v_max_f32_e32 v48, 0, v48
	v_max_f32_e32 v51, 0, v51
	v_max_f32_e32 v50, 0, v50
	ds_write_b128 v147, v[56:59]
	v_pk_mul_f32 v[54:55], v[54:55], v[54:55]
	v_pk_mul_f32 v[52:53], v[52:53], v[52:53]
	v_pk_mul_f32 v[56:57], v[50:51], v[50:51]
	v_pk_mul_f32 v[50:51], v[48:49], v[48:49]
	v_cvt_pk_bf16_f32 v48, v52, v53
	v_cvt_pk_bf16_f32 v49, v54, v55
	v_cvt_pk_bf16_f32 v50, v50, v51
	v_cvt_pk_bf16_f32 v51, v56, v57
	ds_write_b128 v147, v[48:51] offset:64
	ds_read_b128 v[48:51], v148
	ds_read_b128 v[52:55], v148 offset:1152
	v_add_co_u32_e32 v56, vcc, s54, v112
	s_nop 0
	s_nop 0
	v_addc_co_u32_e32 v57, vcc, 0, v113, vcc
	s_waitcnt lgkmcnt(0)
	global_store_dwordx4 v[56:57], v[48:51], off
	s_nop 1
	v_add_co_u32_e32 v48, vcc, s55, v112
	s_nop 4
	v_addc_co_u32_e32 v49, vcc, 0, v113, vcc
	v_max_f32_e32 v45, 0, v45
	v_max_f32_e32 v44, 0, v44
	v_max_f32_e32 v47, 0, v47
	v_max_f32_e32 v46, 0, v46
	v_max_f32_e32 v41, 0, v41
	v_max_f32_e32 v40, 0, v40
	v_max_f32_e32 v43, 0, v43
	v_max_f32_e32 v42, 0, v42
	global_store_dwordx4 v[48:49], v[52:55], off
	v_pk_mul_f32 v[46:47], v[46:47], v[46:47]
	v_pk_mul_f32 v[44:45], v[44:45], v[44:45]
	v_pk_mul_f32 v[48:49], v[42:43], v[42:43]
	v_pk_mul_f32 v[42:43], v[40:41], v[40:41]
	s_nop 7
	v_cvt_pk_bf16_f32 v40, v44, v45
	v_cvt_pk_bf16_f32 v41, v46, v47
	v_cvt_pk_bf16_f32 v42, v42, v43
	v_cvt_pk_bf16_f32 v43, v48, v49
	v_max_f32_e32 v37, 0, v37
	v_max_f32_e32 v36, 0, v36
	v_max_f32_e32 v39, 0, v39
	v_max_f32_e32 v38, 0, v38
	v_max_f32_e32 v33, 0, v33
	v_max_f32_e32 v32, 0, v32
	v_max_f32_e32 v35, 0, v35
	v_max_f32_e32 v34, 0, v34
	ds_write_b128 v147, v[40:43]
	v_pk_mul_f32 v[38:39], v[38:39], v[38:39]
	v_pk_mul_f32 v[36:37], v[36:37], v[36:37]
	v_pk_mul_f32 v[40:41], v[34:35], v[34:35]
	v_pk_mul_f32 v[34:35], v[32:33], v[32:33]
	v_cvt_pk_bf16_f32 v32, v36, v37
	v_cvt_pk_bf16_f32 v33, v38, v39
	v_cvt_pk_bf16_f32 v34, v34, v35
	v_cvt_pk_bf16_f32 v35, v40, v41
	ds_write_b128 v147, v[32:35] offset:64
	ds_read_b128 v[32:35], v148
	ds_read_b128 v[36:39], v148 offset:1152
	v_add_co_u32_e32 v40, vcc, s56, v112
	s_nop 0
	s_nop 0
	v_addc_co_u32_e32 v41, vcc, 0, v113, vcc
	s_waitcnt lgkmcnt(0)
	global_store_dwordx4 v[40:41], v[32:35], off
	s_nop 1
	v_add_co_u32_e32 v32, vcc, s57, v112
	s_nop 4
	v_addc_co_u32_e32 v33, vcc, 0, v113, vcc
	v_max_f32_e32 v29, 0, v29
	v_max_f32_e32 v28, 0, v28
	v_max_f32_e32 v31, 0, v31
	v_max_f32_e32 v30, 0, v30
	v_max_f32_e32 v25, 0, v25
	v_max_f32_e32 v24, 0, v24
	v_max_f32_e32 v27, 0, v27
	v_max_f32_e32 v26, 0, v26
	global_store_dwordx4 v[32:33], v[36:39], off
	v_pk_mul_f32 v[30:31], v[30:31], v[30:31]
	v_pk_mul_f32 v[28:29], v[28:29], v[28:29]
	v_pk_mul_f32 v[32:33], v[26:27], v[26:27]
	v_pk_mul_f32 v[26:27], v[24:25], v[24:25]
	s_nop 7
	v_cvt_pk_bf16_f32 v24, v28, v29
	v_cvt_pk_bf16_f32 v25, v30, v31
	v_cvt_pk_bf16_f32 v26, v26, v27
	v_cvt_pk_bf16_f32 v27, v32, v33
	v_max_f32_e32 v21, 0, v21
	v_max_f32_e32 v20, 0, v20
	v_max_f32_e32 v23, 0, v23
	v_max_f32_e32 v22, 0, v22
	v_max_f32_e32 v17, 0, v17
	v_max_f32_e32 v16, 0, v16
	v_max_f32_e32 v19, 0, v19
	v_max_f32_e32 v18, 0, v18
	ds_write_b128 v147, v[24:27]
	v_pk_mul_f32 v[22:23], v[22:23], v[22:23]
	v_pk_mul_f32 v[20:21], v[20:21], v[20:21]
	v_pk_mul_f32 v[24:25], v[18:19], v[18:19]
	v_pk_mul_f32 v[18:19], v[16:17], v[16:17]
	v_cvt_pk_bf16_f32 v16, v20, v21
	v_cvt_pk_bf16_f32 v17, v22, v23
	v_cvt_pk_bf16_f32 v18, v18, v19
	v_cvt_pk_bf16_f32 v19, v24, v25
	ds_write_b128 v147, v[16:19] offset:64
	ds_read_b128 v[16:19], v148
	ds_read_b128 v[20:23], v148 offset:1152
	v_add_co_u32_e32 v24, vcc, s58, v112
	s_nop 0
	s_nop 0
	v_addc_co_u32_e32 v25, vcc, 0, v113, vcc
	s_waitcnt lgkmcnt(0)
	global_store_dwordx4 v[24:25], v[16:19], off
	s_nop 1
	v_add_co_u32_e32 v16, vcc, s59, v112
	s_nop 4
	v_addc_co_u32_e32 v17, vcc, 0, v113, vcc
	v_max_f32_e32 v13, 0, v13
	v_max_f32_e32 v12, 0, v12
	v_max_f32_e32 v15, 0, v15
	v_max_f32_e32 v14, 0, v14
	v_max_f32_e32 v9, 0, v9
	v_max_f32_e32 v8, 0, v8
	v_max_f32_e32 v11, 0, v11
	v_max_f32_e32 v10, 0, v10
	global_store_dwordx4 v[16:17], v[20:23], off
	v_pk_mul_f32 v[14:15], v[14:15], v[14:15]
	v_pk_mul_f32 v[12:13], v[12:13], v[12:13]
	v_pk_mul_f32 v[16:17], v[10:11], v[10:11]
	v_pk_mul_f32 v[10:11], v[8:9], v[8:9]
	s_nop 7
	v_cvt_pk_bf16_f32 v8, v12, v13
	v_cvt_pk_bf16_f32 v9, v14, v15
	v_cvt_pk_bf16_f32 v10, v10, v11
	v_cvt_pk_bf16_f32 v11, v16, v17
	v_max_f32_e32 v5, 0, v5
	v_max_f32_e32 v4, 0, v4
	v_max_f32_e32 v7, 0, v7
	v_max_f32_e32 v6, 0, v6
	v_max_f32_e32 v1, 0, v1
	v_max_f32_e32 v0, 0, v0
	v_max_f32_e32 v3, 0, v3
	v_max_f32_e32 v2, 0, v2
	ds_write_b128 v147, v[8:11]
	v_pk_mul_f32 v[6:7], v[6:7], v[6:7]
	v_pk_mul_f32 v[4:5], v[4:5], v[4:5]
	v_pk_mul_f32 v[8:9], v[2:3], v[2:3]
	v_pk_mul_f32 v[2:3], v[0:1], v[0:1]
	v_cvt_pk_bf16_f32 v0, v4, v5
	v_cvt_pk_bf16_f32 v1, v6, v7
	v_cvt_pk_bf16_f32 v2, v2, v3
	v_cvt_pk_bf16_f32 v3, v8, v9
	ds_write_b128 v147, v[0:3] offset:64
	ds_read_b128 v[0:3], v148
	ds_read_b128 v[4:7], v148 offset:1152
	v_add_co_u32_e32 v8, vcc, 0x160000, v112
	s_nop 1
	v_addc_co_u32_e32 v9, vcc, 0, v113, vcc
	s_waitcnt lgkmcnt(0)
	global_store_dwordx4 v[8:9], v[0:3], off
	s_nop 1
	v_add_co_u32_e32 v0, vcc, 0x170000, v112
	s_nop 1
	v_addc_co_u32_e32 v1, vcc, 0, v113, vcc
	s_andn2_b64 vcc, exec, s[0:1]
	s_mov_b64 s[0:1], -1
	global_store_dwordx4 v[0:1], v[4:7], off
	s_cbranch_vccnz .LBB0_891
	s_andn2_b64 vcc, exec, s[10:11]
	s_cbranch_vccnz .LBB0_890
	s_barrier
	s_branch .LBB0_890
